# FoX softmax: cross-half row max / row sum exchange via v_permlane32_swap (VALU) instead of ds_bpermute + lgkmcnt wait on the serial softmax chain
# speedup vs baseline: 1.0010x; 1.0010x over previous
; #define LAS __attribute__((address_space(3)))
; template <bool PEND> DI void fx_softmax(f32x16& p0, f32x16& p1, f32x16& q0, f32x16& q1, bf16x8 (&pw)[4], f32x16 (&o)[2], float& m, float& l, float& cqm, float cq, LAS float* al,
;                                         int k0, int qw0, int qrow, int r32, int hi) {
;     ...
;     float rm = fmaxf(fmaxf(p0[0], p1[0]), fmaxf(p0[1], p1[1]));
; #pragma unroll
;     for (int i = 2; i < 16; i += 2) { rm = fmaxf(fmaxf(rm, p0[i]), p1[i]); rm = fmaxf(fmaxf(rm, p0[i + 1]), p1[i + 1]); }
;     rm = fmaxf(rm, __shfl_xor(rm, 32));
;     if (__any(rm > 0.f)) {
;         const float dl = fmaxf(rm, 0.f), alpha = __builtin_amdgcn_exp2f(-dl); l *= alpha; m += dl; cqm = cq - m;
; #pragma unroll
;         for (int i = 0; i < 16; ++i) { p0[i] -= dl; p1[i] -= dl; }
;         if (PEND) {
; #pragma unroll
;             for (int i = 0; i < 16; ++i) { q0[i] -= dl; q1[i] -= dl; } }
;         if (hi == 0) al[r32] = alpha;
;         asm volatile("s_waitcnt lgkmcnt(0)" ::: "memory");
; #pragma unroll
;         for (int g = 0; g < 4; ++g) { const f32x4 a4 = *(const LAS f32x4*)(al + 8 * g + 4 * hi);
; #pragma unroll
;             for (int e = 0; e < 4; ++e) { o[0][4 * g + e] *= a4[e]; o[1][4 * g + e] *= a4[e]; } }
.LBB0_532:
	s_nop 7
	v_max_f32_e32 v66, v51, v51
	v_max_f32_e32 v67, v35, v35
	v_max_f32_e32 v66, v67, v66
	v_max3_f32 v66, v34, v50, v66
	v_max3_f32 v66, v66, v36, v52
	v_max3_f32 v66, v66, v37, v53
	v_max3_f32 v66, v66, v38, v54
	v_max3_f32 v66, v66, v39, v55
	v_max3_f32 v66, v66, v40, v56
	v_max3_f32 v66, v66, v41, v57
	v_max3_f32 v66, v66, v42, v58
	v_max3_f32 v66, v66, v43, v59
	v_max3_f32 v66, v66, v44, v60
	v_max3_f32 v66, v66, v45, v61
	v_max3_f32 v66, v66, v46, v62
	v_max3_f32 v66, v66, v47, v63
	v_max3_f32 v66, v66, v48, v64
	v_max3_f32 v66, v66, v49, v65
	v_mov_b32_e32 v67, v66
	v_mov_b32_e32 v239, v66
	s_nop 1
	v_permlane32_swap_b32_e32 v67, v239
	v_mov_b64_e32 v[96:97], v[16:17]
	v_mov_b32_e32 v174, v226
	v_mov_b32_e32 v176, v227
	v_mov_b32_e32 v175, v228
	s_waitcnt lgkmcnt(0)
	v_max_f32_e32 v67, v67, v239
	v_max_f32_e32 v177, v66, v67
	v_mov_b64_e32 v[80:81], v[32:33]
	v_cmp_lt_f32_e32 vcc, 0, v177
	v_mov_b64_e32 v[94:95], v[14:15]
	v_mov_b64_e32 v[92:93], v[12:13]
	v_mov_b64_e32 v[90:91], v[10:11]
	v_mov_b64_e32 v[88:89], v[8:9]
	v_mov_b64_e32 v[86:87], v[6:7]
	v_mov_b64_e32 v[84:85], v[4:5]
	v_mov_b64_e32 v[82:83], v[2:3]
	v_mov_b64_e32 v[78:79], v[30:31]
	v_mov_b64_e32 v[76:77], v[28:29]
	v_mov_b64_e32 v[74:75], v[26:27]
	v_mov_b64_e32 v[72:73], v[24:25]
	v_mov_b64_e32 v[70:71], v[22:23]
	v_mov_b64_e32 v[68:69], v[20:21]
	v_mov_b64_e32 v[66:67], v[18:19]
	s_cbranch_vccz .LBB0_536
	v_max_f32_e32 v66, v177, v177
	v_max_f32_e32 v66, 0, v66
	v_exp_f32_e64 v67, -v66
	s_and_saveexec_b64 s[42:43], s[40:41]
	ds_write_b32 v216, v67
	s_or_b64 exec, exec, s[42:43]
	v_mul_f32_e32 v176, v227, v67
	v_pk_add_f32 v[34:35], v[34:35], v[66:67] op_sel_hi:[1,0] neg_lo:[0,1] neg_hi:[0,1]
	v_pk_add_f32 v[50:51], v[50:51], v[66:67] op_sel_hi:[1,0] neg_lo:[0,1] neg_hi:[0,1]
	v_pk_add_f32 v[36:37], v[36:37], v[66:67] op_sel_hi:[1,0] neg_lo:[0,1] neg_hi:[0,1]
	v_pk_add_f32 v[52:53], v[52:53], v[66:67] op_sel_hi:[1,0] neg_lo:[0,1] neg_hi:[0,1]
	v_pk_add_f32 v[38:39], v[38:39], v[66:67] op_sel_hi:[1,0] neg_lo:[0,1] neg_hi:[0,1]
	v_pk_add_f32 v[54:55], v[54:55], v[66:67] op_sel_hi:[1,0] neg_lo:[0,1] neg_hi:[0,1]
	v_pk_add_f32 v[40:41], v[40:41], v[66:67] op_sel_hi:[1,0] neg_lo:[0,1] neg_hi:[0,1]
	v_pk_add_f32 v[56:57], v[56:57], v[66:67] op_sel_hi:[1,0] neg_lo:[0,1] neg_hi:[0,1]
	v_pk_add_f32 v[42:43], v[42:43], v[66:67] op_sel_hi:[1,0] neg_lo:[0,1] neg_hi:[0,1]
	v_pk_add_f32 v[58:59], v[58:59], v[66:67] op_sel_hi:[1,0] neg_lo:[0,1] neg_hi:[0,1]
	v_pk_add_f32 v[44:45], v[44:45], v[66:67] op_sel_hi:[1,0] neg_lo:[0,1] neg_hi:[0,1]
	v_pk_add_f32 v[60:61], v[60:61], v[66:67] op_sel_hi:[1,0] neg_lo:[0,1] neg_hi:[0,1]
	v_pk_add_f32 v[46:47], v[46:47], v[66:67] op_sel_hi:[1,0] neg_lo:[0,1] neg_hi:[0,1]
	v_pk_add_f32 v[62:63], v[62:63], v[66:67] op_sel_hi:[1,0] neg_lo:[0,1] neg_hi:[0,1]
	s_waitcnt lgkmcnt(0)
	v_add_u32_e32 v67, s30, v0
	ds_read_b128 v[82:85], v67 offset:64
	ds_read_b128 v[86:89], v67 offset:96
	ds_read_b128 v[178:181], v67
	ds_read_b128 v[182:185], v67 offset:32
	v_add_f32_e32 v174, v226, v66
	v_sub_f32_e32 v175, v220, v174
	v_pk_add_f32 v[48:49], v[48:49], v[66:67] op_sel_hi:[1,0] neg_lo:[0,1] neg_hi:[0,1]
	v_pk_add_f32 v[64:65], v[64:65], v[66:67] op_sel_hi:[1,0] neg_lo:[0,1] neg_hi:[0,1]
	s_waitcnt lgkmcnt(2)
	v_pk_mul_f32 v[78:79], v[30:31], v[86:87]
	v_pk_mul_f32 v[74:75], v[26:27], v[82:83]
	s_waitcnt lgkmcnt(0)
	v_pk_mul_f32 v[70:71], v[22:23], v[182:183]
	v_pk_mul_f32 v[80:81], v[32:33], v[88:89]
	v_pk_mul_f32 v[76:77], v[28:29], v[84:85]
	v_pk_mul_f32 v[72:73], v[24:25], v[184:185]
	v_pk_mul_f32 v[68:69], v[20:21], v[180:181]
	v_pk_mul_f32 v[66:67], v[18:19], v[178:179]
	v_pk_mul_f32 v[94:95], v[14:15], v[86:87]
	v_pk_mul_f32 v[90:91], v[10:11], v[82:83]
	v_pk_mul_f32 v[86:87], v[6:7], v[182:183]
	v_pk_mul_f32 v[96:97], v[16:17], v[88:89]
	v_pk_mul_f32 v[92:93], v[12:13], v[84:85]
	v_pk_mul_f32 v[88:89], v[8:9], v[184:185]
	v_pk_mul_f32 v[84:85], v[4:5], v[180:181]
	v_pk_mul_f32 v[82:83], v[2:3], v[178:179]

; #define LAS __attribute__((address_space(3)))
; template <bool PEND> DI void fx_softmax(f32x16& p0, f32x16& p1, f32x16& q0, f32x16& q1, bf16x8 (&pw)[4], f32x16 (&o)[2], float& m, float& l, float& cqm, float cq, LAS float* al,
;                                         int k0, int qw0, int qrow, int r32, int hi) {
;     ...
;     float rm = fmaxf(fmaxf(p0[0], p1[0]), fmaxf(p0[1], p1[1]));
; #pragma unroll
;     for (int i = 2; i < 16; i += 2) { rm = fmaxf(fmaxf(rm, p0[i]), p1[i]); rm = fmaxf(fmaxf(rm, p0[i + 1]), p1[i + 1]); }
;     rm = fmaxf(rm, __shfl_xor(rm, 32));
;     if (__any(rm > 0.f)) {
;         const float dl = fmaxf(rm, 0.f), alpha = __builtin_amdgcn_exp2f(-dl); l *= alpha; m += dl; cqm = cq - m;
; #pragma unroll
;         for (int i = 0; i < 16; ++i) { p0[i] -= dl; p1[i] -= dl; }
;         if (PEND) {
; #pragma unroll
;             for (int i = 0; i < 16; ++i) { q0[i] -= dl; q1[i] -= dl; } }
;         if (hi == 0) al[r32] = alpha;
;         asm volatile("s_waitcnt lgkmcnt(0)" ::: "memory");
; #pragma unroll
;         for (int g = 0; g < 4; ++g) { const f32x4 a4 = *(const LAS f32x4*)(al + 8 * g + 4 * hi);
; #pragma unroll
;             for (int e = 0; e < 4; ++e) { o[0][4 * g + e] *= a4[e]; o[1][4 * g + e] *= a4[e]; } }
.LBB0_544:
	v_max_f32_e32 v174, v83, v83
	v_max_f32_e32 v175, v67, v67
	v_max_f32_e32 v174, v175, v174
	v_max3_f32 v174, v66, v82, v174
	v_max3_f32 v174, v174, v68, v84
	v_max3_f32 v174, v174, v69, v85
	v_max3_f32 v174, v174, v70, v86
	v_max3_f32 v174, v174, v71, v87
	v_max3_f32 v174, v174, v72, v88
	v_max3_f32 v174, v174, v73, v89
	v_max3_f32 v174, v174, v74, v90
	v_max3_f32 v174, v174, v75, v91
	v_max3_f32 v174, v174, v76, v92
	v_max3_f32 v174, v174, v77, v93
	v_max3_f32 v174, v174, v78, v94
	v_max3_f32 v174, v174, v79, v95
	v_max3_f32 v174, v174, v80, v96
	v_max3_f32 v174, v174, v81, v97
	v_mov_b32_e32 v175, v174
	v_mov_b32_e32 v239, v174
	s_nop 1
	v_permlane32_swap_b32_e32 v175, v239
	s_waitcnt lgkmcnt(0)
	v_max_f32_e32 v175, v175, v239
	v_max_f32_e32 v174, v174, v175
	v_cmp_lt_f32_e32 vcc, 0, v174
	s_cbranch_vccz .LBB0_548
	v_max_f32_e32 v174, v174, v174
	v_max_f32_e32 v174, 0, v174
	v_exp_f32_e64 v175, -v174
	s_and_saveexec_b64 s[42:43], s[40:41]
	ds_write_b32 v216, v175
	s_or_b64 exec, exec, s[42:43]
	s_waitcnt lgkmcnt(0)
	v_add_u32_e32 v186, s30, v0
	v_mul_f32_e32 v227, v227, v175
	v_add_f32_e32 v226, v226, v174
	v_pk_add_f32 v[66:67], v[66:67], v[174:175] op_sel_hi:[1,0] neg_lo:[0,1] neg_hi:[0,1]
	v_pk_add_f32 v[82:83], v[82:83], v[174:175] op_sel_hi:[1,0] neg_lo:[0,1] neg_hi:[0,1]
	v_pk_add_f32 v[68:69], v[68:69], v[174:175] op_sel_hi:[1,0] neg_lo:[0,1] neg_hi:[0,1]
	v_pk_add_f32 v[84:85], v[84:85], v[174:175] op_sel_hi:[1,0] neg_lo:[0,1] neg_hi:[0,1]
	v_pk_add_f32 v[70:71], v[70:71], v[174:175] op_sel_hi:[1,0] neg_lo:[0,1] neg_hi:[0,1]
	v_pk_add_f32 v[86:87], v[86:87], v[174:175] op_sel_hi:[1,0] neg_lo:[0,1] neg_hi:[0,1]
	v_pk_add_f32 v[72:73], v[72:73], v[174:175] op_sel_hi:[1,0] neg_lo:[0,1] neg_hi:[0,1]
	v_pk_add_f32 v[88:89], v[88:89], v[174:175] op_sel_hi:[1,0] neg_lo:[0,1] neg_hi:[0,1]
	v_pk_add_f32 v[74:75], v[74:75], v[174:175] op_sel_hi:[1,0] neg_lo:[0,1] neg_hi:[0,1]
	v_pk_add_f32 v[90:91], v[90:91], v[174:175] op_sel_hi:[1,0] neg_lo:[0,1] neg_hi:[0,1]
	v_pk_add_f32 v[76:77], v[76:77], v[174:175] op_sel_hi:[1,0] neg_lo:[0,1] neg_hi:[0,1]
	v_pk_add_f32 v[92:93], v[92:93], v[174:175] op_sel_hi:[1,0] neg_lo:[0,1] neg_hi:[0,1]
	v_pk_add_f32 v[78:79], v[78:79], v[174:175] op_sel_hi:[1,0] neg_lo:[0,1] neg_hi:[0,1]
	v_pk_add_f32 v[94:95], v[94:95], v[174:175] op_sel_hi:[1,0] neg_lo:[0,1] neg_hi:[0,1]
	v_pk_add_f32 v[80:81], v[80:81], v[174:175] op_sel_hi:[1,0] neg_lo:[0,1] neg_hi:[0,1]
	v_pk_add_f32 v[96:97], v[96:97], v[174:175] op_sel_hi:[1,0] neg_lo:[0,1] neg_hi:[0,1]
	v_sub_f32_e32 v49, v49, v174
	v_sub_f32_e32 v48, v48, v174
	v_sub_f32_e32 v47, v47, v174
	v_sub_f32_e32 v46, v46, v174
	v_sub_f32_e32 v45, v45, v174
	v_sub_f32_e32 v44, v44, v174
	v_sub_f32_e32 v43, v43, v174
	v_sub_f32_e32 v42, v42, v174
	v_sub_f32_e32 v41, v41, v174
	v_sub_f32_e32 v40, v40, v174
	v_sub_f32_e32 v39, v39, v174
	v_sub_f32_e32 v38, v38, v174
	v_sub_f32_e32 v37, v37, v174
	v_sub_f32_e32 v36, v36, v174
	v_sub_f32_e32 v35, v35, v174
	v_sub_f32_e32 v34, v34, v174
	v_sub_f32_e32 v65, v65, v174
	v_sub_f32_e32 v64, v64, v174
	v_sub_f32_e32 v63, v63, v174
	v_sub_f32_e32 v62, v62, v174
	v_sub_f32_e32 v61, v61, v174
	v_sub_f32_e32 v60, v60, v174
	v_sub_f32_e32 v59, v59, v174
	v_sub_f32_e32 v58, v58, v174
	v_sub_f32_e32 v57, v57, v174
	v_sub_f32_e32 v56, v56, v174
	v_sub_f32_e32 v55, v55, v174
	v_sub_f32_e32 v54, v54, v174
	v_sub_f32_e32 v53, v53, v174
	v_sub_f32_e32 v52, v52, v174
	v_sub_f32_e32 v51, v51, v174
	v_sub_f32_e32 v50, v50, v174
	ds_read_b128 v[174:177], v186
	ds_read_b128 v[178:181], v186 offset:32
	ds_read_b128 v[182:185], v186 offset:64
	ds_read_b128 v[186:189], v186 offset:96
	v_sub_f32_e32 v228, v220, v226
	s_waitcnt lgkmcnt(2)
	v_pk_mul_f32 v[22:23], v[22:23], v[178:179]
	s_waitcnt lgkmcnt(1)
	v_pk_mul_f32 v[26:27], v[26:27], v[182:183]
	s_waitcnt lgkmcnt(0)
	v_pk_mul_f32 v[30:31], v[30:31], v[186:187]
	v_pk_mul_f32 v[32:33], v[32:33], v[188:189]
	v_pk_mul_f32 v[28:29], v[28:29], v[184:185]
	v_pk_mul_f32 v[24:25], v[24:25], v[180:181]
	v_pk_mul_f32 v[20:21], v[20:21], v[176:177]
	v_pk_mul_f32 v[18:19], v[18:19], v[174:175]
	v_pk_mul_f32 v[14:15], v[14:15], v[186:187]
	v_pk_mul_f32 v[10:11], v[10:11], v[182:183]
	v_pk_mul_f32 v[6:7], v[6:7], v[178:179]
	v_pk_mul_f32 v[16:17], v[16:17], v[188:189]
	v_pk_mul_f32 v[12:13], v[12:13], v[184:185]
	v_pk_mul_f32 v[8:9], v[8:9], v[180:181]
	v_pk_mul_f32 v[4:5], v[4:5], v[176:177]
	v_pk_mul_f32 v[2:3], v[2:3], v[174:175]

; #define LAS __attribute__((address_space(3)))
; template <bool PEND> DI void fx_softmax(f32x16& p0, f32x16& p1, f32x16& q0, f32x16& q1, bf16x8 (&pw)[4], f32x16 (&o)[2], float& m, float& l, float& cqm, float cq, LAS float* al,
;                                         int k0, int qw0, int qrow, int r32, int hi) {
;     ...
;     float rm = fmaxf(fmaxf(p0[0], p1[0]), fmaxf(p0[1], p1[1]));
; #pragma unroll
;     for (int i = 2; i < 16; i += 2) { rm = fmaxf(fmaxf(rm, p0[i]), p1[i]); rm = fmaxf(fmaxf(rm, p0[i + 1]), p1[i + 1]); }
;     rm = fmaxf(rm, __shfl_xor(rm, 32));
;     if (__any(rm > 0.f)) {
;         const float dl = fmaxf(rm, 0.f), alpha = __builtin_amdgcn_exp2f(-dl); l *= alpha; m += dl; cqm = cq - m;
; #pragma unroll
;         for (int i = 0; i < 16; ++i) { p0[i] -= dl; p1[i] -= dl; }
;         if (PEND) {
; #pragma unroll
;             for (int i = 0; i < 16; ++i) { q0[i] -= dl; q1[i] -= dl; } }
;         if (hi == 0) al[r32] = alpha;
;         asm volatile("s_waitcnt lgkmcnt(0)" ::: "memory");
; #pragma unroll
;         for (int g = 0; g < 4; ++g) { const f32x4 a4 = *(const LAS f32x4*)(al + 8 * g + 4 * hi);
; #pragma unroll
;             for (int e = 0; e < 4; ++e) { o[0][4 * g + e] *= a4[e]; o[1][4 * g + e] *= a4[e]; } }
;         asm volatile("" ::: "memory");
;     }
; #pragma unroll
;     for (int i = 0; i < 16; ++i) { p0[i] = __builtin_amdgcn_exp2f(p0[i]); p1[i] = __builtin_amdgcn_exp2f(p1[i]); }
;     { const f32x16 t = p0 + p1; const f32x4 u4 = (f32x4){t[0], t[1], t[2], t[3]} + (f32x4){t[4], t[5], t[6], t[7]} + (f32x4){t[8], t[9], t[10], t[11]} + (f32x4){t[12], t[13], t[14], t[15]};
;       l += (u4.x + u4.y) + (u4.z + u4.w); }
.LBB0_552:
	v_pk_add_f32 v[140:141], v[184:185], v[182:183]
	v_pk_add_f32 v[142:143], v[180:181], v[178:179]
	v_pk_add_f32 v[134:135], v[196:197], v[194:195]
	v_pk_add_f32 v[140:141], v[142:143], v[140:141]
	v_pk_add_f32 v[132:133], v[200:201], v[198:199]
	v_pk_add_f32 v[134:135], v[134:135], v[140:141]
	v_pk_add_f32 v[138:139], v[188:189], v[186:187]
	v_pk_add_f32 v[132:133], v[132:133], v[134:135]
	v_max_f32_e32 v134, v51, v51
	v_max_f32_e32 v135, v35, v35
	v_max_f32_e32 v134, v135, v134
	v_max3_f32 v134, v34, v50, v134
	v_max3_f32 v134, v134, v36, v52
	v_max3_f32 v134, v134, v37, v53
	v_max3_f32 v134, v134, v38, v54
	v_max3_f32 v134, v134, v39, v55
	v_max3_f32 v134, v134, v40, v56
	v_max3_f32 v134, v134, v41, v57
	v_max3_f32 v134, v134, v42, v58
	v_max3_f32 v134, v134, v43, v59
	v_max3_f32 v134, v134, v44, v60
	v_max3_f32 v134, v134, v45, v61
	v_max3_f32 v134, v134, v46, v62
	v_max3_f32 v134, v134, v47, v63
	v_max3_f32 v134, v134, v48, v64
	v_pk_add_f32 v[144:145], v[176:177], v[174:175]
	v_max3_f32 v134, v134, v49, v65
	v_pk_add_f32 v[136:137], v[192:193], v[190:191]
	v_pk_add_f32 v[138:139], v[144:145], v[138:139]
	v_mov_b32_e32 v135, v134
	v_mov_b32_e32 v239, v134
	s_nop 1
	v_permlane32_swap_b32_e32 v135, v239
	v_pk_add_f32 v[130:131], v[204:205], v[202:203]
	v_pk_add_f32 v[136:137], v[136:137], v[138:139]
	s_nop 0
	v_pk_add_f32 v[130:131], v[130:131], v[136:137]
	s_nop 0
	v_add_f32_e32 v130, v130, v131
	v_add_f32_e32 v131, v132, v133
	v_add_f32_e32 v130, v130, v131
	v_add_f32_e32 v131, v227, v130
	s_waitcnt lgkmcnt(0)
	v_max_f32_e32 v130, v135, v239
	v_max_f32_e32 v130, v134, v130
	v_cmp_lt_f32_e32 vcc, 0, v130
	s_cbranch_vccz .LBB0_556
	v_max_f32_e32 v130, v130, v130
	v_max_f32_e32 v130, 0, v130
	v_exp_f32_e64 v132, -v130
	s_and_saveexec_b64 s[42:43], s[40:41]
	ds_write_b32 v216, v132
	s_or_b64 exec, exec, s[42:43]
	v_mul_f32_e32 v131, v131, v132
	v_add_f32_e32 v174, v226, v130
	v_pk_add_f32 v[34:35], v[34:35], v[130:131] op_sel_hi:[1,0] neg_lo:[0,1] neg_hi:[0,1]
	v_pk_add_f32 v[50:51], v[50:51], v[130:131] op_sel_hi:[1,0] neg_lo:[0,1] neg_hi:[0,1]
	v_pk_add_f32 v[36:37], v[36:37], v[130:131] op_sel_hi:[1,0] neg_lo:[0,1] neg_hi:[0,1]
	v_pk_add_f32 v[52:53], v[52:53], v[130:131] op_sel_hi:[1,0] neg_lo:[0,1] neg_hi:[0,1]
	v_pk_add_f32 v[38:39], v[38:39], v[130:131] op_sel_hi:[1,0] neg_lo:[0,1] neg_hi:[0,1]
	v_pk_add_f32 v[54:55], v[54:55], v[130:131] op_sel_hi:[1,0] neg_lo:[0,1] neg_hi:[0,1]
	v_pk_add_f32 v[40:41], v[40:41], v[130:131] op_sel_hi:[1,0] neg_lo:[0,1] neg_hi:[0,1]
	v_pk_add_f32 v[56:57], v[56:57], v[130:131] op_sel_hi:[1,0] neg_lo:[0,1] neg_hi:[0,1]
	v_pk_add_f32 v[42:43], v[42:43], v[130:131] op_sel_hi:[1,0] neg_lo:[0,1] neg_hi:[0,1]
	v_pk_add_f32 v[58:59], v[58:59], v[130:131] op_sel_hi:[1,0] neg_lo:[0,1] neg_hi:[0,1]
	v_pk_add_f32 v[44:45], v[44:45], v[130:131] op_sel_hi:[1,0] neg_lo:[0,1] neg_hi:[0,1]
	v_pk_add_f32 v[60:61], v[60:61], v[130:131] op_sel_hi:[1,0] neg_lo:[0,1] neg_hi:[0,1]
	v_pk_add_f32 v[46:47], v[46:47], v[130:131] op_sel_hi:[1,0] neg_lo:[0,1] neg_hi:[0,1]
	v_pk_add_f32 v[62:63], v[62:63], v[130:131] op_sel_hi:[1,0] neg_lo:[0,1] neg_hi:[0,1]
	v_pk_add_f32 v[48:49], v[48:49], v[130:131] op_sel_hi:[1,0] neg_lo:[0,1] neg_hi:[0,1]
	v_pk_add_f32 v[64:65], v[64:65], v[130:131] op_sel_hi:[1,0] neg_lo:[0,1] neg_hi:[0,1]
	s_waitcnt lgkmcnt(0)
	v_add_u32_e32 v130, s30, v0
	ds_read_b128 v[132:135], v130
	ds_read_b128 v[136:139], v130 offset:32
	ds_read_b128 v[140:143], v130 offset:64
	ds_read_b128 v[144:147], v130 offset:96
	v_sub_f32_e32 v175, v220, v174
	s_waitcnt lgkmcnt(2)
	v_pk_mul_f32 v[22:23], v[22:23], v[136:137]
	s_waitcnt lgkmcnt(1)
	v_pk_mul_f32 v[26:27], v[26:27], v[140:141]
	s_waitcnt lgkmcnt(0)
	v_pk_mul_f32 v[30:31], v[30:31], v[144:145]
	v_pk_mul_f32 v[32:33], v[32:33], v[146:147]
	v_pk_mul_f32 v[28:29], v[28:29], v[142:143]
	v_pk_mul_f32 v[24:25], v[24:25], v[138:139]
	v_pk_mul_f32 v[20:21], v[20:21], v[134:135]
	v_pk_mul_f32 v[18:19], v[18:19], v[132:133]
	v_pk_mul_f32 v[14:15], v[14:15], v[144:145]
	v_pk_mul_f32 v[10:11], v[10:11], v[140:141]
	v_pk_mul_f32 v[6:7], v[6:7], v[136:137]
	v_pk_mul_f32 v[16:17], v[16:17], v[146:147]
	v_pk_mul_f32 v[12:13], v[12:13], v[142:143]
	v_pk_mul_f32 v[8:9], v[8:9], v[138:139]
	v_pk_mul_f32 v[4:5], v[4:5], v[134:135]
	v_pk_mul_f32 v[2:3], v[2:3], v[132:133]
	s_branch .LBB0_557

; DI void fox_unit(int bh, int qb, const Params& p, LAS unsigned char* lds, float thr2) {
;     ...
;     l += __shfl_xor(l, 32);
;     if (hi == 0) al[r32] = 1.0f / l;
.LBB0_564:
	v_mov_b32_e32 v0, v34
	v_mov_b32_e32 v239, v34
	s_nop 1
	v_permlane32_swap_b32_e32 v0, v239
	v_cmp_gt_u32_e32 vcc, 32, v169
	s_and_saveexec_b64 s[22:23], vcc
	s_cbranch_execz .LBB0_506
	s_waitcnt lgkmcnt(0)
	v_add_f32_e32 v0, v34, v239
	v_div_scale_f32 v2, s[8:9], v0, v0, 1.0
	v_rcp_f32_e32 v3, v2
	v_div_scale_f32 v4, vcc, 1.0, v0, 1.0
	v_fma_f32 v5, -v2, v3, 1.0
	v_fmac_f32_e32 v3, v5, v3
	v_mul_f32_e32 v5, v4, v3
	v_fma_f32 v6, -v2, v5, v4
	v_fmac_f32_e32 v5, v6, v3
	v_fma_f32 v2, -v2, v5, v4
	v_div_fmas_f32 v2, v2, v3, v5
	v_div_fixup_f32 v0, v2, v0, 1.0
	ds_write_b32 v216, v0
	s_branch .LBB0_506
